# HGRN2 elementwise waves: q~/k~ rows of two tokens per ds_write2_b64, shorter DPP/lane-swap segment prefix; split 17:15
# speedup vs baseline: 1.0924x; 1.0057x over previous
.LBB0_403:
	v_readlane_b32 s2, v250, 16
	v_readlane_b32 s3, v250, 17
	s_mov_b64 s[0:1], -1
	s_and_b64 vcc, exec, s[2:3]
	v_readlane_b32 s50, v250, 56
	v_readlane_b32 s51, v250, 54
	s_cbranch_vccz .LBB0_439
	s_mov_b64 exec, -1
	s_waitcnt vmcnt(0) lgkmcnt(0)
	v_readlane_b32 s0, v250, 18
	v_readfirstlane_b32 s6, v0
	v_and_b32_e32 v1, 63, v0
	s_lshr_b32 s6, s6, 6
	s_ashr_i32 s1, s0, 2
	s_and_b32 s2, s0, 3
	s_and_b32 s3, s1, 3
	s_bfe_u32 s4, s1, 0x20002
	s_lshr_b32 s5, s1, 4
	v_lshlrev_b32_e32 v2, 2, v0
	v_add_u32_e32 v2, 0x1e800, v2
	v_mov_b32_e32 v3, 0
	ds_write_b32 v2, v3
	ds_write_b32 v2, v3 offset:2048
	ds_write_b32 v2, v3 offset:4096
	ds_write_b32 v2, v3 offset:6144
	ds_write_b32 v2, v3 offset:8192
	s_cmp_eq_u32 s5, 0
	s_cselect_b64 s[36:37], -1, 0
	s_cmp_lt_u32 s6, 4
	s_cbranch_scc0 .Lhg_sinit
	v_and_b32_e32 v20, 7, v1
	v_lshrrev_b32_e32 v21, 3, v1
	s_lshl_b32 s7, s6, 5
	v_lshl_add_u32 v22, v20, 2, s7
	v_lshlrev_b32_e32 v23, 3, v21
	v_sub_u32_e32 v24, 0xfff, v23
	s_mov_b64 vcc, s[36:37]
	v_cndmask_b32_e32 v23, v24, v23, vcc
	v_mul_u32_u24_e32 v2, 0x2600, v23
	v_lshl_add_u32 v2, v22, 1, v2
	s_lshl_b32 s7, s5, 10
	s_add_i32 s7, s7, 0x400
	v_add_u32_e32 v3, s7, v2
	s_mul_i32 s7, s4, 0x2600000
	s_lshl_b32 s8, s3, 8
	s_add_i32 s7, s7, s8
	s_add_i32 s7, s7, 0x101200
	s_add_u32 s8, s98, s7
	s_addc_u32 s9, s99, 0
	s_lshl_b32 s7, s5, 1
	s_sub_i32 s7, 1, s7
	s_mul_i32 s10, s7, 0x2600
	s_ashr_i32 s11, s10, 31
	s_mul_i32 s12, s7, 0x85000
	s_ashr_i32 s13, s12, 31
	s_mul_i32 s14, s7, 0xfffed000
	s_ashr_i32 s15, s14, 31
	s_mov_b32 s16, 0
	v_mul_u32_u24_e32 v4, 0x900, v21
	v_lshl_add_u32 v4, v22, 1, v4
	v_add_u32_e32 v6, 0x4800, v4
	v_add_u32_e32 v7, 0x9000, v4
	v_add_u32_e32 v9, 0xd800, v4
	v_xor_b32_e32 v5, v21, v20
	v_lshlrev_b32_e32 v5, 4, v5
	v_mul_u32_u24_e32 v24, 0xa0, v22
	v_add_u32_e32 v5, v5, v24
	v_add_u32_e32 v5, 0x12000, v5
	s_lshl_b32 s7, s6, 10
	v_lshlrev_b32_e32 v8, 2, v22
	v_add_u32_e32 v8, 0x24000, v8
	s_mov_b64 s[18:19], -1
	s_lshl_b64 s[18:19], s[18:19], 8
	s_mov_b64 s[20:21], -1
	s_lshl_b64 s[20:21], s[20:21], 16
	s_mov_b64 s[22:23], -1
	s_lshl_b64 s[22:23], s[22:23], 24
	s_mov_b64 s[24:25], -1
	s_lshl_b64 s[24:25], s[24:25], 32
	s_mov_b64 s[26:27], -1
	s_lshl_b64 s[26:27], s[26:27], 40
	s_mov_b64 s[28:29], -1
	s_lshl_b64 s[28:29], s[28:29], 48
	s_mov_b64 s[30:31], -1
	s_lshl_b64 s[30:31], s[30:31], 56
	global_load_dwordx2 v[10:11], v3, s[8:9]
	global_load_dwordx2 v[26:27], v2, s[8:9]
	s_add_u32 s8, s8, s10
	s_addc_u32 s9, s9, s11
	global_load_dwordx2 v[12:13], v3, s[8:9]
	global_load_dwordx2 v[28:29], v2, s[8:9]
	s_add_u32 s8, s8, s10
	s_addc_u32 s9, s9, s11
	global_load_dwordx2 v[14:15], v3, s[8:9]
	global_load_dwordx2 v[30:31], v2, s[8:9]
	s_add_u32 s8, s8, s10
	s_addc_u32 s9, s9, s11
	global_load_dwordx2 v[16:17], v3, s[8:9]
	global_load_dwordx2 v[32:33], v2, s[8:9]
	s_add_u32 s8, s8, s10
	s_addc_u32 s9, s9, s11
	global_load_dwordx2 v[18:19], v3, s[8:9]
	global_load_dwordx2 v[34:35], v2, s[8:9]
	s_add_u32 s8, s8, s10
	s_addc_u32 s9, s9, s11
	global_load_dwordx2 v[20:21], v3, s[8:9]
	global_load_dwordx2 v[36:37], v2, s[8:9]
	s_add_u32 s8, s8, s10
	s_addc_u32 s9, s9, s11
	global_load_dwordx2 v[22:23], v3, s[8:9]
	global_load_dwordx2 v[38:39], v2, s[8:9]
	s_add_u32 s8, s8, s10
	s_addc_u32 s9, s9, s11
	global_load_dwordx2 v[24:25], v3, s[8:9]
	global_load_dwordx2 v[40:41], v2, s[8:9]
	s_add_u32 s8, s8, s10
	s_addc_u32 s9, s9, s11
	s_cmp_lt_u32 s16, 63
	s_cselect_b32 s34, s12, s14
	s_cselect_b32 s35, s13, s15
	s_add_u32 s8, s8, s34
	s_addc_u32 s9, s9, s35
	s_add_i32 s16, s16, 1
	global_load_dwordx2 v[42:43], v3, s[8:9]
	global_load_dwordx2 v[58:59], v2, s[8:9]
	s_add_u32 s8, s8, s10
	s_addc_u32 s9, s9, s11
	global_load_dwordx2 v[44:45], v3, s[8:9]
	global_load_dwordx2 v[60:61], v2, s[8:9]
	s_add_u32 s8, s8, s10
	s_addc_u32 s9, s9, s11
	global_load_dwordx2 v[46:47], v3, s[8:9]
	global_load_dwordx2 v[62:63], v2, s[8:9]
	s_add_u32 s8, s8, s10
	s_addc_u32 s9, s9, s11
	global_load_dwordx2 v[48:49], v3, s[8:9]
	global_load_dwordx2 v[64:65], v2, s[8:9]
	s_add_u32 s8, s8, s10
	s_addc_u32 s9, s9, s11
	global_load_dwordx2 v[50:51], v3, s[8:9]
	global_load_dwordx2 v[66:67], v2, s[8:9]
	s_add_u32 s8, s8, s10
	s_addc_u32 s9, s9, s11
	global_load_dwordx2 v[52:53], v3, s[8:9]
	global_load_dwordx2 v[68:69], v2, s[8:9]
	s_add_u32 s8, s8, s10
	s_addc_u32 s9, s9, s11
	global_load_dwordx2 v[54:55], v3, s[8:9]
	global_load_dwordx2 v[70:71], v2, s[8:9]
	s_add_u32 s8, s8, s10
	s_addc_u32 s9, s9, s11
	global_load_dwordx2 v[56:57], v3, s[8:9]
	global_load_dwordx2 v[72:73], v2, s[8:9]
	s_add_u32 s8, s8, s10
	s_addc_u32 s9, s9, s11
	s_cmp_lt_u32 s16, 63
	s_cselect_b32 s34, s12, s14
	s_cselect_b32 s35, s13, s15
	s_add_u32 s8, s8, s34
	s_addc_u32 s9, s9, s35
	s_add_i32 s16, s16, 1
	s_waitcnt vmcnt(0)
	s_waitcnt lgkmcnt(0)
	s_barrier
	s_mov_b64 s[38:39], exec
	v_readlane_b32 s40, v250, 10
	v_readlane_b32 s41, v250, 11
	s_and_b64 s[40:41], s[38:39], s[40:41]
	s_mov_b64 exec, s[40:41]
	s_cbranch_execz .Lhg_rel0
	s_mov_b64 s[40:41], exec
	v_mbcnt_lo_u32_b32 v224, s40, 0
	buffer_wbl2 sc1
	s_waitcnt vmcnt(0)
	v_mbcnt_hi_u32_b32 v224, s41, v224
	v_cmp_eq_u32_e32 vcc, 0, v224
	s_and_b64 s[42:43], exec, vcc
	s_mov_b64 exec, s[42:43]
	s_cbranch_execz .Lhg_rel0
	s_bcnt1_i32_b64 s42, s[40:41]
	s_lshl_b32 s40, s1, 7
	s_add_u32 s40, s98, s40
	s_addc_u32 s41, s99, 0
	v_mov_b32_e32 v224, 0x2000
	v_mov_b32_e32 v225, s42
	global_atomic_add v224, v225, s[40:41]
.Lhg_rel0:
	s_or_b64 exec, exec, s[38:39]
	s_waitcnt vmcnt(16)
	v_lshlrev_b32_e32 v76, 16, v10
	v_and_b32_e32 v77, 0xffff0000, v10
	v_lshlrev_b32_e32 v78, 16, v11
	v_and_b32_e32 v79, 0xffff0000, v11
	v_lshlrev_b32_e32 v80, 16, v12
	v_and_b32_e32 v81, 0xffff0000, v12
	v_lshlrev_b32_e32 v82, 16, v13
	v_and_b32_e32 v83, 0xffff0000, v13
	v_lshlrev_b32_e32 v84, 16, v14
	v_and_b32_e32 v85, 0xffff0000, v14
	v_lshlrev_b32_e32 v86, 16, v15
	v_and_b32_e32 v87, 0xffff0000, v15
	v_lshlrev_b32_e32 v88, 16, v16
	v_and_b32_e32 v89, 0xffff0000, v16
	v_lshlrev_b32_e32 v90, 16, v17
	v_and_b32_e32 v91, 0xffff0000, v17
	v_lshlrev_b32_e32 v92, 16, v18
	v_and_b32_e32 v93, 0xffff0000, v18
	v_lshlrev_b32_e32 v94, 16, v19
	v_and_b32_e32 v95, 0xffff0000, v19
	v_lshlrev_b32_e32 v96, 16, v20
	v_and_b32_e32 v97, 0xffff0000, v20
	v_lshlrev_b32_e32 v98, 16, v21
	v_and_b32_e32 v99, 0xffff0000, v21
	v_lshlrev_b32_e32 v100, 16, v22
	v_and_b32_e32 v101, 0xffff0000, v22
	v_lshlrev_b32_e32 v102, 16, v23
	v_and_b32_e32 v103, 0xffff0000, v23
	v_lshlrev_b32_e32 v104, 16, v24
	v_and_b32_e32 v105, 0xffff0000, v24
	v_lshlrev_b32_e32 v106, 16, v25
	v_and_b32_e32 v107, 0xffff0000, v25
	v_pk_add_f32 v[140:141], v[76:77], 1.0 op_sel_hi:[1,0] neg_lo:[1,0] neg_hi:[1,0]
	v_pk_add_f32 v[142:143], v[78:79], 1.0 op_sel_hi:[1,0] neg_lo:[1,0] neg_hi:[1,0]
	v_pk_add_f32 v[226:227], v[80:81], 1.0 op_sel_hi:[1,0] neg_lo:[1,0] neg_hi:[1,0]
	v_pk_add_f32 v[228:229], v[82:83], 1.0 op_sel_hi:[1,0] neg_lo:[1,0] neg_hi:[1,0]
	v_pk_mul_f32 v[144:145], v[140:141], v[226:227]
	v_pk_mul_f32 v[146:147], v[142:143], v[228:229]
	v_pk_add_f32 v[230:231], v[84:85], 1.0 op_sel_hi:[1,0] neg_lo:[1,0] neg_hi:[1,0]
	v_pk_add_f32 v[232:233], v[86:87], 1.0 op_sel_hi:[1,0] neg_lo:[1,0] neg_hi:[1,0]
	v_pk_mul_f32 v[148:149], v[144:145], v[230:231]
	v_pk_mul_f32 v[150:151], v[146:147], v[232:233]
	v_pk_add_f32 v[234:235], v[88:89], 1.0 op_sel_hi:[1,0] neg_lo:[1,0] neg_hi:[1,0]
	v_pk_add_f32 v[236:237], v[90:91], 1.0 op_sel_hi:[1,0] neg_lo:[1,0] neg_hi:[1,0]
	v_pk_mul_f32 v[152:153], v[148:149], v[234:235]
	v_pk_mul_f32 v[154:155], v[150:151], v[236:237]
	v_pk_add_f32 v[238:239], v[92:93], 1.0 op_sel_hi:[1,0] neg_lo:[1,0] neg_hi:[1,0]
	v_pk_add_f32 v[240:241], v[94:95], 1.0 op_sel_hi:[1,0] neg_lo:[1,0] neg_hi:[1,0]
	v_pk_mul_f32 v[156:157], v[152:153], v[238:239]
	v_pk_mul_f32 v[158:159], v[154:155], v[240:241]
	v_pk_add_f32 v[242:243], v[96:97], 1.0 op_sel_hi:[1,0] neg_lo:[1,0] neg_hi:[1,0]
	v_pk_add_f32 v[244:245], v[98:99], 1.0 op_sel_hi:[1,0] neg_lo:[1,0] neg_hi:[1,0]
	v_pk_mul_f32 v[160:161], v[156:157], v[242:243]
	v_pk_mul_f32 v[162:163], v[158:159], v[244:245]
	v_pk_add_f32 v[246:247], v[100:101], 1.0 op_sel_hi:[1,0] neg_lo:[1,0] neg_hi:[1,0]
	v_pk_add_f32 v[248:249], v[102:103], 1.0 op_sel_hi:[1,0] neg_lo:[1,0] neg_hi:[1,0]
	v_pk_mul_f32 v[164:165], v[160:161], v[246:247]
	v_pk_mul_f32 v[166:167], v[162:163], v[248:249]
	v_pk_add_f32 v[74:75], v[104:105], 1.0 op_sel_hi:[1,0] neg_lo:[1,0] neg_hi:[1,0]
	v_pk_add_f32 v[172:173], v[106:107], 1.0 op_sel_hi:[1,0] neg_lo:[1,0] neg_hi:[1,0]
	v_pk_mul_f32 v[168:169], v[164:165], v[74:75]
	v_pk_mul_f32 v[170:171], v[166:167], v[172:173]
	v_lshlrev_b32_e32 v108, 16, v26
	v_and_b32_e32 v109, 0xffff0000, v26
	v_lshlrev_b32_e32 v110, 16, v27
	v_and_b32_e32 v111, 0xffff0000, v27
	v_lshlrev_b32_e32 v112, 16, v28
	v_and_b32_e32 v113, 0xffff0000, v28
	v_lshlrev_b32_e32 v114, 16, v29
	v_and_b32_e32 v115, 0xffff0000, v29
	v_lshlrev_b32_e32 v116, 16, v30
	v_and_b32_e32 v117, 0xffff0000, v30
	v_lshlrev_b32_e32 v118, 16, v31
	v_and_b32_e32 v119, 0xffff0000, v31
	v_lshlrev_b32_e32 v120, 16, v32
	v_and_b32_e32 v121, 0xffff0000, v32
	v_lshlrev_b32_e32 v122, 16, v33
	v_and_b32_e32 v123, 0xffff0000, v33
	v_lshlrev_b32_e32 v124, 16, v34
	v_and_b32_e32 v125, 0xffff0000, v34
	v_lshlrev_b32_e32 v126, 16, v35
	v_and_b32_e32 v127, 0xffff0000, v35
	v_lshlrev_b32_e32 v128, 16, v36
	v_and_b32_e32 v129, 0xffff0000, v36
	v_lshlrev_b32_e32 v130, 16, v37
	v_and_b32_e32 v131, 0xffff0000, v37
	v_lshlrev_b32_e32 v132, 16, v38
	v_and_b32_e32 v133, 0xffff0000, v38
	v_lshlrev_b32_e32 v134, 16, v39
	v_and_b32_e32 v135, 0xffff0000, v39
	v_lshlrev_b32_e32 v136, 16, v40
	v_and_b32_e32 v137, 0xffff0000, v40
	v_lshlrev_b32_e32 v138, 16, v41
	v_and_b32_e32 v139, 0xffff0000, v41
	global_load_dwordx2 v[10:11], v3, s[8:9]
	global_load_dwordx2 v[26:27], v2, s[8:9]
	s_add_u32 s8, s8, s10
	s_addc_u32 s9, s9, s11
	global_load_dwordx2 v[12:13], v3, s[8:9]
	global_load_dwordx2 v[28:29], v2, s[8:9]
	s_add_u32 s8, s8, s10
	s_addc_u32 s9, s9, s11
	global_load_dwordx2 v[14:15], v3, s[8:9]
	global_load_dwordx2 v[30:31], v2, s[8:9]
	s_add_u32 s8, s8, s10
	s_addc_u32 s9, s9, s11
	global_load_dwordx2 v[16:17], v3, s[8:9]
	global_load_dwordx2 v[32:33], v2, s[8:9]
	s_add_u32 s8, s8, s10
	s_addc_u32 s9, s9, s11
	global_load_dwordx2 v[18:19], v3, s[8:9]
	global_load_dwordx2 v[34:35], v2, s[8:9]
	s_add_u32 s8, s8, s10
	s_addc_u32 s9, s9, s11
	global_load_dwordx2 v[20:21], v3, s[8:9]
	global_load_dwordx2 v[36:37], v2, s[8:9]
	s_add_u32 s8, s8, s10
	s_addc_u32 s9, s9, s11
	global_load_dwordx2 v[22:23], v3, s[8:9]
	global_load_dwordx2 v[38:39], v2, s[8:9]
	s_add_u32 s8, s8, s10
	s_addc_u32 s9, s9, s11
	global_load_dwordx2 v[24:25], v3, s[8:9]
	global_load_dwordx2 v[40:41], v2, s[8:9]
	s_add_u32 s8, s8, s10
	s_addc_u32 s9, s9, s11
	s_cmp_lt_u32 s16, 63
	s_cselect_b32 s34, s12, s14
	s_cselect_b32 s35, s13, s15
	s_add_u32 s8, s8, s34
	s_addc_u32 s9, s9, s35
	s_add_i32 s16, s16, 1
	v_mov_b32_e32 v176, 1.0
	v_mov_b32_e32 v177, 1.0
	v_mov_b32_e32 v178, 1.0
	v_mov_b32_e32 v179, 1.0
	v_mul_f32_dpp v196, v168, v168 row_ror:8 row_mask:0xf bank_mask:0xf
	v_mul_f32_dpp v197, v169, v169 row_ror:8 row_mask:0xf bank_mask:0xf
	v_mul_f32_dpp v198, v170, v170 row_ror:8 row_mask:0xf bank_mask:0xf
	v_mul_f32_dpp v199, v171, v171 row_ror:8 row_mask:0xf bank_mask:0xf
	v_mov_b32_dpp v176, v168 row_shr:8 row_mask:0xf bank_mask:0xc
	v_mov_b32_dpp v177, v169 row_shr:8 row_mask:0xf bank_mask:0xc
	v_mov_b32_dpp v178, v170 row_shr:8 row_mask:0xf bank_mask:0xc
	v_mov_b32_dpp v179, v171 row_shr:8 row_mask:0xf bank_mask:0xc
	v_mov_b32_e32 v200, v196
	v_mov_b32_e32 v201, v197
	v_mov_b32_e32 v202, v198
	v_mov_b32_e32 v203, v199
	v_permlane16_swap_b32_e32 v196, v200
	v_permlane16_swap_b32_e32 v197, v201
	v_permlane16_swap_b32_e32 v198, v202
	v_permlane16_swap_b32_e32 v199, v203
	v_pk_mul_f32 v[204:205], v[196:197], v[200:201]
	v_pk_mul_f32 v[206:207], v[198:199], v[202:203]
	v_mov_b32_e32 v208, v204
	v_mov_b32_e32 v209, v205
	v_mov_b32_e32 v210, v206
	v_mov_b32_e32 v211, v207
	s_nop 0
	v_permlane32_swap_b32_e32 v204, v208
	v_permlane32_swap_b32_e32 v205, v209
	v_permlane32_swap_b32_e32 v206, v210
	v_permlane32_swap_b32_e32 v207, v211
	s_mov_b64 s[34:35], exec
	s_mov_b64 exec, 0xffff0000
	v_pk_mul_f32 v[176:177], v[176:177], v[196:197]
	v_pk_mul_f32 v[178:179], v[178:179], v[198:199]
	s_mov_b32 exec_lo, 0
	s_mov_b32 exec_hi, -1
	v_pk_mul_f32 v[176:177], v[176:177], v[204:205]
	v_pk_mul_f32 v[178:179], v[178:179], v[206:207]
	s_mov_b32 exec_hi, 0xffff0000
	v_pk_mul_f32 v[176:177], v[176:177], v[196:197]
	v_pk_mul_f32 v[178:179], v[178:179], v[198:199]
	s_mov_b64 exec, s[34:35]
	v_pk_mul_f32 v[188:189], v[176:177], v[168:169]
	v_pk_mul_f32 v[190:191], v[178:179], v[170:171]
	s_mov_b64 s[34:35], exec
	s_mov_b64 exec, s[30:31]
	ds_write_b128 v8, v[188:191]
	s_mov_b64 exec, s[34:35]
	v_max_f32_e32 v180, 0xda24260, v188
	v_max_f32_e32 v181, 0xda24260, v189
	v_max_f32_e32 v182, 0xda24260, v190
	v_max_f32_e32 v183, 0xda24260, v191
	v_rcp_f32_e32 v180, v180
	v_rcp_f32_e32 v181, v181
	v_rcp_f32_e32 v182, v182
	v_rcp_f32_e32 v183, v183
	v_pk_mul_f32 v[192:193], v[136:137], v[188:189]
	v_pk_mul_f32 v[194:195], v[138:139], v[190:191]
	v_pk_mul_f32 v[196:197], v[104:105], v[180:181]
	v_pk_mul_f32 v[198:199], v[106:107], v[182:183]
	v_cvt_pk_bf16_f32 v208, v192, v193
	v_cvt_pk_bf16_f32 v209, v194, v195
	v_cvt_pk_bf16_f32 v210, v196, v197
	v_cvt_pk_bf16_f32 v211, v198, v199
	v_pk_mul_f32 v[180:181], v[180:181], v[74:75]
	v_pk_mul_f32 v[182:183], v[182:183], v[172:173]
	v_pk_mul_f32 v[188:189], v[176:177], v[164:165]
	v_pk_mul_f32 v[190:191], v[178:179], v[166:167]
	v_pk_mul_f32 v[192:193], v[132:133], v[188:189]
	v_pk_mul_f32 v[194:195], v[134:135], v[190:191]
	v_pk_mul_f32 v[200:201], v[100:101], v[180:181]
	v_pk_mul_f32 v[202:203], v[102:103], v[182:183]
	v_cvt_pk_bf16_f32 v204, v192, v193
	v_cvt_pk_bf16_f32 v205, v194, v195
	v_cvt_pk_bf16_f32 v206, v200, v201
	v_cvt_pk_bf16_f32 v207, v202, v203
	ds_write2_b64 v4, v[204:205], v[208:209] offset0:216 offset1:252
	ds_write2_b64 v7, v[206:207], v[210:211] offset0:216 offset1:252
	v_pk_mul_f32 v[180:181], v[180:181], v[246:247]
	v_pk_mul_f32 v[182:183], v[182:183], v[248:249]
	v_pk_mul_f32 v[188:189], v[176:177], v[160:161]
	v_pk_mul_f32 v[190:191], v[178:179], v[162:163]
	v_pk_mul_f32 v[192:193], v[128:129], v[188:189]
	v_pk_mul_f32 v[194:195], v[130:131], v[190:191]
	v_pk_mul_f32 v[196:197], v[96:97], v[180:181]
	v_pk_mul_f32 v[198:199], v[98:99], v[182:183]
	v_cvt_pk_bf16_f32 v208, v192, v193
	v_cvt_pk_bf16_f32 v209, v194, v195
	v_cvt_pk_bf16_f32 v210, v196, v197
	v_cvt_pk_bf16_f32 v211, v198, v199
	v_pk_mul_f32 v[180:181], v[180:181], v[242:243]
	v_pk_mul_f32 v[182:183], v[182:183], v[244:245]
	v_pk_mul_f32 v[188:189], v[176:177], v[156:157]
	v_pk_mul_f32 v[190:191], v[178:179], v[158:159]
	v_pk_mul_f32 v[192:193], v[124:125], v[188:189]
	v_pk_mul_f32 v[194:195], v[126:127], v[190:191]
	v_pk_mul_f32 v[200:201], v[92:93], v[180:181]
	v_pk_mul_f32 v[202:203], v[94:95], v[182:183]
	v_cvt_pk_bf16_f32 v204, v192, v193
	v_cvt_pk_bf16_f32 v205, v194, v195
	v_cvt_pk_bf16_f32 v206, v200, v201
	v_cvt_pk_bf16_f32 v207, v202, v203
	ds_write2_b64 v4, v[204:205], v[208:209] offset0:144 offset1:180
	ds_write2_b64 v7, v[206:207], v[210:211] offset0:144 offset1:180
	v_pk_mul_f32 v[180:181], v[180:181], v[238:239]
	v_pk_mul_f32 v[182:183], v[182:183], v[240:241]
	v_pk_mul_f32 v[188:189], v[176:177], v[152:153]
	v_pk_mul_f32 v[190:191], v[178:179], v[154:155]
	v_pk_mul_f32 v[192:193], v[120:121], v[188:189]
	v_pk_mul_f32 v[194:195], v[122:123], v[190:191]
	v_pk_mul_f32 v[196:197], v[88:89], v[180:181]
	v_pk_mul_f32 v[198:199], v[90:91], v[182:183]
	v_cvt_pk_bf16_f32 v208, v192, v193
	v_cvt_pk_bf16_f32 v209, v194, v195
	v_cvt_pk_bf16_f32 v210, v196, v197
	v_cvt_pk_bf16_f32 v211, v198, v199
	v_pk_mul_f32 v[180:181], v[180:181], v[234:235]
	v_pk_mul_f32 v[182:183], v[182:183], v[236:237]
	v_pk_mul_f32 v[188:189], v[176:177], v[148:149]
	v_pk_mul_f32 v[190:191], v[178:179], v[150:151]
	v_pk_mul_f32 v[192:193], v[116:117], v[188:189]
	v_pk_mul_f32 v[194:195], v[118:119], v[190:191]
	v_pk_mul_f32 v[200:201], v[84:85], v[180:181]
	v_pk_mul_f32 v[202:203], v[86:87], v[182:183]
	v_cvt_pk_bf16_f32 v204, v192, v193
	v_cvt_pk_bf16_f32 v205, v194, v195
	v_cvt_pk_bf16_f32 v206, v200, v201
	v_cvt_pk_bf16_f32 v207, v202, v203
	ds_write2_b64 v4, v[204:205], v[208:209] offset0:72 offset1:108
	ds_write2_b64 v7, v[206:207], v[210:211] offset0:72 offset1:108
	v_pk_mul_f32 v[180:181], v[180:181], v[230:231]
	v_pk_mul_f32 v[182:183], v[182:183], v[232:233]
	v_pk_mul_f32 v[188:189], v[176:177], v[144:145]
	v_pk_mul_f32 v[190:191], v[178:179], v[146:147]
	v_pk_mul_f32 v[192:193], v[112:113], v[188:189]
	v_pk_mul_f32 v[194:195], v[114:115], v[190:191]
	v_pk_mul_f32 v[196:197], v[80:81], v[180:181]
	v_pk_mul_f32 v[198:199], v[82:83], v[182:183]
	v_cvt_pk_bf16_f32 v208, v192, v193
	v_cvt_pk_bf16_f32 v209, v194, v195
	v_cvt_pk_bf16_f32 v210, v196, v197
	v_cvt_pk_bf16_f32 v211, v198, v199
	v_pk_mul_f32 v[180:181], v[180:181], v[226:227]
	v_pk_mul_f32 v[182:183], v[182:183], v[228:229]
	v_pk_mul_f32 v[188:189], v[176:177], v[140:141]
	v_pk_mul_f32 v[190:191], v[178:179], v[142:143]
	v_pk_mul_f32 v[192:193], v[108:109], v[188:189]
	v_pk_mul_f32 v[194:195], v[110:111], v[190:191]
	v_pk_mul_f32 v[200:201], v[76:77], v[180:181]
	v_pk_mul_f32 v[202:203], v[78:79], v[182:183]
	v_cvt_pk_bf16_f32 v204, v192, v193
	v_cvt_pk_bf16_f32 v205, v194, v195
	v_cvt_pk_bf16_f32 v206, v200, v201
	v_cvt_pk_bf16_f32 v207, v202, v203
	ds_write2_b64 v4, v[204:205], v[208:209] offset0:0 offset1:36
	ds_write2_b64 v7, v[206:207], v[210:211] offset0:0 offset1:36
	s_waitcnt vmcnt(16)
	v_lshlrev_b32_e32 v76, 16, v42
	v_and_b32_e32 v77, 0xffff0000, v42
	v_lshlrev_b32_e32 v78, 16, v43
	v_and_b32_e32 v79, 0xffff0000, v43
	v_lshlrev_b32_e32 v80, 16, v44
	v_and_b32_e32 v81, 0xffff0000, v44
	v_lshlrev_b32_e32 v82, 16, v45
	v_and_b32_e32 v83, 0xffff0000, v45
	v_lshlrev_b32_e32 v84, 16, v46
	v_and_b32_e32 v85, 0xffff0000, v46
	v_lshlrev_b32_e32 v86, 16, v47
	v_and_b32_e32 v87, 0xffff0000, v47
	v_lshlrev_b32_e32 v88, 16, v48
	v_and_b32_e32 v89, 0xffff0000, v48
	v_lshlrev_b32_e32 v90, 16, v49
	v_and_b32_e32 v91, 0xffff0000, v49
	v_lshlrev_b32_e32 v92, 16, v50
	v_and_b32_e32 v93, 0xffff0000, v50
	v_lshlrev_b32_e32 v94, 16, v51
	v_and_b32_e32 v95, 0xffff0000, v51
	v_lshlrev_b32_e32 v96, 16, v52
	v_and_b32_e32 v97, 0xffff0000, v52
	v_lshlrev_b32_e32 v98, 16, v53
	v_and_b32_e32 v99, 0xffff0000, v53
	v_lshlrev_b32_e32 v100, 16, v54
	v_and_b32_e32 v101, 0xffff0000, v54
	v_lshlrev_b32_e32 v102, 16, v55
	v_and_b32_e32 v103, 0xffff0000, v55
	v_lshlrev_b32_e32 v104, 16, v56
	v_and_b32_e32 v105, 0xffff0000, v56
	v_lshlrev_b32_e32 v106, 16, v57
	v_and_b32_e32 v107, 0xffff0000, v57
	v_pk_add_f32 v[140:141], v[76:77], 1.0 op_sel_hi:[1,0] neg_lo:[1,0] neg_hi:[1,0]
	v_pk_add_f32 v[142:143], v[78:79], 1.0 op_sel_hi:[1,0] neg_lo:[1,0] neg_hi:[1,0]
	v_pk_add_f32 v[226:227], v[80:81], 1.0 op_sel_hi:[1,0] neg_lo:[1,0] neg_hi:[1,0]
	v_pk_add_f32 v[228:229], v[82:83], 1.0 op_sel_hi:[1,0] neg_lo:[1,0] neg_hi:[1,0]
	v_pk_mul_f32 v[144:145], v[140:141], v[226:227]
	v_pk_mul_f32 v[146:147], v[142:143], v[228:229]
	v_pk_add_f32 v[230:231], v[84:85], 1.0 op_sel_hi:[1,0] neg_lo:[1,0] neg_hi:[1,0]
	v_pk_add_f32 v[232:233], v[86:87], 1.0 op_sel_hi:[1,0] neg_lo:[1,0] neg_hi:[1,0]
	v_pk_mul_f32 v[148:149], v[144:145], v[230:231]
	v_pk_mul_f32 v[150:151], v[146:147], v[232:233]
	v_pk_add_f32 v[234:235], v[88:89], 1.0 op_sel_hi:[1,0] neg_lo:[1,0] neg_hi:[1,0]
	v_pk_add_f32 v[236:237], v[90:91], 1.0 op_sel_hi:[1,0] neg_lo:[1,0] neg_hi:[1,0]
	v_pk_mul_f32 v[152:153], v[148:149], v[234:235]
	v_pk_mul_f32 v[154:155], v[150:151], v[236:237]
	v_pk_add_f32 v[238:239], v[92:93], 1.0 op_sel_hi:[1,0] neg_lo:[1,0] neg_hi:[1,0]
	v_pk_add_f32 v[240:241], v[94:95], 1.0 op_sel_hi:[1,0] neg_lo:[1,0] neg_hi:[1,0]
	v_pk_mul_f32 v[156:157], v[152:153], v[238:239]
	v_pk_mul_f32 v[158:159], v[154:155], v[240:241]
	v_pk_add_f32 v[242:243], v[96:97], 1.0 op_sel_hi:[1,0] neg_lo:[1,0] neg_hi:[1,0]
	v_pk_add_f32 v[244:245], v[98:99], 1.0 op_sel_hi:[1,0] neg_lo:[1,0] neg_hi:[1,0]
	v_pk_mul_f32 v[160:161], v[156:157], v[242:243]
	v_pk_mul_f32 v[162:163], v[158:159], v[244:245]
	v_pk_add_f32 v[246:247], v[100:101], 1.0 op_sel_hi:[1,0] neg_lo:[1,0] neg_hi:[1,0]
	v_pk_add_f32 v[248:249], v[102:103], 1.0 op_sel_hi:[1,0] neg_lo:[1,0] neg_hi:[1,0]
	v_pk_mul_f32 v[164:165], v[160:161], v[246:247]
	v_pk_mul_f32 v[166:167], v[162:163], v[248:249]
	v_pk_add_f32 v[74:75], v[104:105], 1.0 op_sel_hi:[1,0] neg_lo:[1,0] neg_hi:[1,0]
	v_pk_add_f32 v[172:173], v[106:107], 1.0 op_sel_hi:[1,0] neg_lo:[1,0] neg_hi:[1,0]
	v_pk_mul_f32 v[168:169], v[164:165], v[74:75]
	v_pk_mul_f32 v[170:171], v[166:167], v[172:173]
	s_waitcnt lgkmcnt(0)
	s_barrier
	s_mov_b32 s17, 31
.Lhg_ploop:
	v_lshlrev_b32_e32 v108, 16, v58
	v_and_b32_e32 v109, 0xffff0000, v58
	v_lshlrev_b32_e32 v110, 16, v59
	v_and_b32_e32 v111, 0xffff0000, v59
	v_lshlrev_b32_e32 v112, 16, v60
	v_and_b32_e32 v113, 0xffff0000, v60
	v_lshlrev_b32_e32 v114, 16, v61
	v_and_b32_e32 v115, 0xffff0000, v61
	v_lshlrev_b32_e32 v116, 16, v62
	v_and_b32_e32 v117, 0xffff0000, v62
	v_lshlrev_b32_e32 v118, 16, v63
	v_and_b32_e32 v119, 0xffff0000, v63
	v_lshlrev_b32_e32 v120, 16, v64
	v_and_b32_e32 v121, 0xffff0000, v64
	v_lshlrev_b32_e32 v122, 16, v65
	v_and_b32_e32 v123, 0xffff0000, v65
	v_lshlrev_b32_e32 v124, 16, v66
	v_and_b32_e32 v125, 0xffff0000, v66
	v_lshlrev_b32_e32 v126, 16, v67
	v_and_b32_e32 v127, 0xffff0000, v67
	v_lshlrev_b32_e32 v128, 16, v68
	v_and_b32_e32 v129, 0xffff0000, v68
	v_lshlrev_b32_e32 v130, 16, v69
	v_and_b32_e32 v131, 0xffff0000, v69
	v_lshlrev_b32_e32 v132, 16, v70
	v_and_b32_e32 v133, 0xffff0000, v70
	v_lshlrev_b32_e32 v134, 16, v71
	v_and_b32_e32 v135, 0xffff0000, v71
	v_lshlrev_b32_e32 v136, 16, v72
	v_and_b32_e32 v137, 0xffff0000, v72
	v_lshlrev_b32_e32 v138, 16, v73
	v_and_b32_e32 v139, 0xffff0000, v73
	global_load_dwordx2 v[42:43], v3, s[8:9]
	global_load_dwordx2 v[58:59], v2, s[8:9]
	s_add_u32 s8, s8, s10
	s_addc_u32 s9, s9, s11
	global_load_dwordx2 v[44:45], v3, s[8:9]
	global_load_dwordx2 v[60:61], v2, s[8:9]
	s_add_u32 s8, s8, s10
	s_addc_u32 s9, s9, s11
	global_load_dwordx2 v[46:47], v3, s[8:9]
	global_load_dwordx2 v[62:63], v2, s[8:9]
	s_add_u32 s8, s8, s10
	s_addc_u32 s9, s9, s11
	global_load_dwordx2 v[48:49], v3, s[8:9]
	global_load_dwordx2 v[64:65], v2, s[8:9]
	s_add_u32 s8, s8, s10
	s_addc_u32 s9, s9, s11
	global_load_dwordx2 v[50:51], v3, s[8:9]
	global_load_dwordx2 v[66:67], v2, s[8:9]
	s_add_u32 s8, s8, s10
	s_addc_u32 s9, s9, s11
	global_load_dwordx2 v[52:53], v3, s[8:9]
	global_load_dwordx2 v[68:69], v2, s[8:9]
	s_add_u32 s8, s8, s10
	s_addc_u32 s9, s9, s11
	global_load_dwordx2 v[54:55], v3, s[8:9]
	global_load_dwordx2 v[70:71], v2, s[8:9]
	s_add_u32 s8, s8, s10
	s_addc_u32 s9, s9, s11
	global_load_dwordx2 v[56:57], v3, s[8:9]
	global_load_dwordx2 v[72:73], v2, s[8:9]
	s_add_u32 s8, s8, s10
	s_addc_u32 s9, s9, s11
	s_cmp_lt_u32 s16, 63
	s_cselect_b32 s34, s12, s14
	s_cselect_b32 s35, s13, s15
	s_add_u32 s8, s8, s34
	s_addc_u32 s9, s9, s35
	s_add_i32 s16, s16, 1
	v_mov_b32_e32 v176, 1.0
	v_mov_b32_e32 v177, 1.0
	v_mov_b32_e32 v178, 1.0
	v_mov_b32_e32 v179, 1.0
	v_mul_f32_dpp v196, v168, v168 row_ror:8 row_mask:0xf bank_mask:0xf
	v_mul_f32_dpp v197, v169, v169 row_ror:8 row_mask:0xf bank_mask:0xf
	v_mul_f32_dpp v198, v170, v170 row_ror:8 row_mask:0xf bank_mask:0xf
	v_mul_f32_dpp v199, v171, v171 row_ror:8 row_mask:0xf bank_mask:0xf
	v_mov_b32_dpp v176, v168 row_shr:8 row_mask:0xf bank_mask:0xc
	v_mov_b32_dpp v177, v169 row_shr:8 row_mask:0xf bank_mask:0xc
	v_mov_b32_dpp v178, v170 row_shr:8 row_mask:0xf bank_mask:0xc
	v_mov_b32_dpp v179, v171 row_shr:8 row_mask:0xf bank_mask:0xc
	v_mov_b32_e32 v200, v196
	v_mov_b32_e32 v201, v197
	v_mov_b32_e32 v202, v198
	v_mov_b32_e32 v203, v199
	v_permlane16_swap_b32_e32 v196, v200
	v_permlane16_swap_b32_e32 v197, v201
	v_permlane16_swap_b32_e32 v198, v202
	v_permlane16_swap_b32_e32 v199, v203
	v_pk_mul_f32 v[204:205], v[196:197], v[200:201]
	v_pk_mul_f32 v[206:207], v[198:199], v[202:203]
	v_mov_b32_e32 v208, v204
	v_mov_b32_e32 v209, v205
	v_mov_b32_e32 v210, v206
	v_mov_b32_e32 v211, v207
	s_nop 0
	v_permlane32_swap_b32_e32 v204, v208
	v_permlane32_swap_b32_e32 v205, v209
	v_permlane32_swap_b32_e32 v206, v210
	v_permlane32_swap_b32_e32 v207, v211
	s_mov_b64 s[34:35], exec
	s_mov_b64 exec, 0xffff0000
	v_pk_mul_f32 v[176:177], v[176:177], v[196:197]
	v_pk_mul_f32 v[178:179], v[178:179], v[198:199]
	s_mov_b32 exec_lo, 0
	s_mov_b32 exec_hi, -1
	v_pk_mul_f32 v[176:177], v[176:177], v[204:205]
	v_pk_mul_f32 v[178:179], v[178:179], v[206:207]
	s_mov_b32 exec_hi, 0xffff0000
	v_pk_mul_f32 v[176:177], v[176:177], v[196:197]
	v_pk_mul_f32 v[178:179], v[178:179], v[198:199]
	s_mov_b64 exec, s[34:35]
	v_pk_mul_f32 v[188:189], v[176:177], v[168:169]
	v_pk_mul_f32 v[190:191], v[178:179], v[170:171]
	s_mov_b64 s[34:35], exec
	s_mov_b64 exec, s[30:31]
	ds_write_b128 v8, v[188:191] offset:512
	s_mov_b64 exec, s[34:35]
	v_max_f32_e32 v180, 0xda24260, v188
	v_max_f32_e32 v181, 0xda24260, v189
	v_max_f32_e32 v182, 0xda24260, v190
	v_max_f32_e32 v183, 0xda24260, v191
	v_rcp_f32_e32 v180, v180
	v_rcp_f32_e32 v181, v181
	v_rcp_f32_e32 v182, v182
	v_rcp_f32_e32 v183, v183
	v_pk_mul_f32 v[192:193], v[136:137], v[188:189]
	v_pk_mul_f32 v[194:195], v[138:139], v[190:191]
	v_pk_mul_f32 v[196:197], v[104:105], v[180:181]
	v_pk_mul_f32 v[198:199], v[106:107], v[182:183]
	v_cvt_pk_bf16_f32 v208, v192, v193
	v_cvt_pk_bf16_f32 v209, v194, v195
	v_cvt_pk_bf16_f32 v210, v196, v197
	v_cvt_pk_bf16_f32 v211, v198, v199
	v_pk_mul_f32 v[180:181], v[180:181], v[74:75]
	v_pk_mul_f32 v[182:183], v[182:183], v[172:173]
	v_pk_mul_f32 v[188:189], v[176:177], v[164:165]
	v_pk_mul_f32 v[190:191], v[178:179], v[166:167]
	v_pk_mul_f32 v[192:193], v[132:133], v[188:189]
	v_pk_mul_f32 v[194:195], v[134:135], v[190:191]
	v_pk_mul_f32 v[200:201], v[100:101], v[180:181]
	v_pk_mul_f32 v[202:203], v[102:103], v[182:183]
	v_cvt_pk_bf16_f32 v204, v192, v193
	v_cvt_pk_bf16_f32 v205, v194, v195
	v_cvt_pk_bf16_f32 v206, v200, v201
	v_cvt_pk_bf16_f32 v207, v202, v203
	ds_write2_b64 v6, v[204:205], v[208:209] offset0:216 offset1:252
	ds_write2_b64 v9, v[206:207], v[210:211] offset0:216 offset1:252
	v_pk_mul_f32 v[180:181], v[180:181], v[246:247]
	v_pk_mul_f32 v[182:183], v[182:183], v[248:249]
	v_pk_mul_f32 v[188:189], v[176:177], v[160:161]
	v_pk_mul_f32 v[190:191], v[178:179], v[162:163]
	v_pk_mul_f32 v[192:193], v[128:129], v[188:189]
	v_pk_mul_f32 v[194:195], v[130:131], v[190:191]
	v_pk_mul_f32 v[196:197], v[96:97], v[180:181]
	v_pk_mul_f32 v[198:199], v[98:99], v[182:183]
	v_cvt_pk_bf16_f32 v208, v192, v193
	v_cvt_pk_bf16_f32 v209, v194, v195
	v_cvt_pk_bf16_f32 v210, v196, v197
	v_cvt_pk_bf16_f32 v211, v198, v199
	v_pk_mul_f32 v[180:181], v[180:181], v[242:243]
	v_pk_mul_f32 v[182:183], v[182:183], v[244:245]
	v_pk_mul_f32 v[188:189], v[176:177], v[156:157]
	v_pk_mul_f32 v[190:191], v[178:179], v[158:159]
	v_pk_mul_f32 v[192:193], v[124:125], v[188:189]
	v_pk_mul_f32 v[194:195], v[126:127], v[190:191]
	v_pk_mul_f32 v[200:201], v[92:93], v[180:181]
	v_pk_mul_f32 v[202:203], v[94:95], v[182:183]
	v_cvt_pk_bf16_f32 v204, v192, v193
	v_cvt_pk_bf16_f32 v205, v194, v195
	v_cvt_pk_bf16_f32 v206, v200, v201
	v_cvt_pk_bf16_f32 v207, v202, v203
	ds_write2_b64 v6, v[204:205], v[208:209] offset0:144 offset1:180
	ds_write2_b64 v9, v[206:207], v[210:211] offset0:144 offset1:180
	v_pk_mul_f32 v[180:181], v[180:181], v[238:239]
	v_pk_mul_f32 v[182:183], v[182:183], v[240:241]
	v_pk_mul_f32 v[188:189], v[176:177], v[152:153]
	v_pk_mul_f32 v[190:191], v[178:179], v[154:155]
	v_pk_mul_f32 v[192:193], v[120:121], v[188:189]
	v_pk_mul_f32 v[194:195], v[122:123], v[190:191]
	v_pk_mul_f32 v[196:197], v[88:89], v[180:181]
	v_pk_mul_f32 v[198:199], v[90:91], v[182:183]
	v_cvt_pk_bf16_f32 v208, v192, v193
	v_cvt_pk_bf16_f32 v209, v194, v195
	v_cvt_pk_bf16_f32 v210, v196, v197
	v_cvt_pk_bf16_f32 v211, v198, v199
	v_pk_mul_f32 v[180:181], v[180:181], v[234:235]
	v_pk_mul_f32 v[182:183], v[182:183], v[236:237]
	v_pk_mul_f32 v[188:189], v[176:177], v[148:149]
	v_pk_mul_f32 v[190:191], v[178:179], v[150:151]
	v_pk_mul_f32 v[192:193], v[116:117], v[188:189]
	v_pk_mul_f32 v[194:195], v[118:119], v[190:191]
	v_pk_mul_f32 v[200:201], v[84:85], v[180:181]
	v_pk_mul_f32 v[202:203], v[86:87], v[182:183]
	v_cvt_pk_bf16_f32 v204, v192, v193
	v_cvt_pk_bf16_f32 v205, v194, v195
	v_cvt_pk_bf16_f32 v206, v200, v201
	v_cvt_pk_bf16_f32 v207, v202, v203
	ds_write2_b64 v6, v[204:205], v[208:209] offset0:72 offset1:108
	ds_write2_b64 v9, v[206:207], v[210:211] offset0:72 offset1:108
	v_pk_mul_f32 v[180:181], v[180:181], v[230:231]
	v_pk_mul_f32 v[182:183], v[182:183], v[232:233]
	v_pk_mul_f32 v[188:189], v[176:177], v[144:145]
	v_pk_mul_f32 v[190:191], v[178:179], v[146:147]
	v_pk_mul_f32 v[192:193], v[112:113], v[188:189]
	v_pk_mul_f32 v[194:195], v[114:115], v[190:191]
	v_pk_mul_f32 v[196:197], v[80:81], v[180:181]
	v_pk_mul_f32 v[198:199], v[82:83], v[182:183]
	v_cvt_pk_bf16_f32 v208, v192, v193
	v_cvt_pk_bf16_f32 v209, v194, v195
	v_cvt_pk_bf16_f32 v210, v196, v197
	v_cvt_pk_bf16_f32 v211, v198, v199
	v_pk_mul_f32 v[180:181], v[180:181], v[226:227]
	v_pk_mul_f32 v[182:183], v[182:183], v[228:229]
	v_pk_mul_f32 v[188:189], v[176:177], v[140:141]
	v_pk_mul_f32 v[190:191], v[178:179], v[142:143]
	v_pk_mul_f32 v[192:193], v[108:109], v[188:189]
	v_pk_mul_f32 v[194:195], v[110:111], v[190:191]
	v_pk_mul_f32 v[200:201], v[76:77], v[180:181]
	v_pk_mul_f32 v[202:203], v[78:79], v[182:183]
	v_cvt_pk_bf16_f32 v204, v192, v193
	v_cvt_pk_bf16_f32 v205, v194, v195
	v_cvt_pk_bf16_f32 v206, v200, v201
	v_cvt_pk_bf16_f32 v207, v202, v203
	ds_write2_b64 v6, v[204:205], v[208:209] offset0:0 offset1:36
	ds_write2_b64 v9, v[206:207], v[210:211] offset0:0 offset1:36
	s_waitcnt vmcnt(16)
	v_lshlrev_b32_e32 v76, 16, v10
	v_and_b32_e32 v77, 0xffff0000, v10
	v_lshlrev_b32_e32 v78, 16, v11
	v_and_b32_e32 v79, 0xffff0000, v11
	v_lshlrev_b32_e32 v80, 16, v12
	v_and_b32_e32 v81, 0xffff0000, v12
	v_lshlrev_b32_e32 v82, 16, v13
	v_and_b32_e32 v83, 0xffff0000, v13
	v_lshlrev_b32_e32 v84, 16, v14
	v_and_b32_e32 v85, 0xffff0000, v14
	v_lshlrev_b32_e32 v86, 16, v15
	v_and_b32_e32 v87, 0xffff0000, v15
	v_lshlrev_b32_e32 v88, 16, v16
	v_and_b32_e32 v89, 0xffff0000, v16
	v_lshlrev_b32_e32 v90, 16, v17
	v_and_b32_e32 v91, 0xffff0000, v17
	v_lshlrev_b32_e32 v92, 16, v18
	v_and_b32_e32 v93, 0xffff0000, v18
	v_lshlrev_b32_e32 v94, 16, v19
	v_and_b32_e32 v95, 0xffff0000, v19
	v_lshlrev_b32_e32 v96, 16, v20
	v_and_b32_e32 v97, 0xffff0000, v20
	v_lshlrev_b32_e32 v98, 16, v21
	v_and_b32_e32 v99, 0xffff0000, v21
	v_lshlrev_b32_e32 v100, 16, v22
	v_and_b32_e32 v101, 0xffff0000, v22
	v_lshlrev_b32_e32 v102, 16, v23
	v_and_b32_e32 v103, 0xffff0000, v23
	v_lshlrev_b32_e32 v104, 16, v24
	v_and_b32_e32 v105, 0xffff0000, v24
	v_lshlrev_b32_e32 v106, 16, v25
	v_and_b32_e32 v107, 0xffff0000, v25
	v_pk_add_f32 v[140:141], v[76:77], 1.0 op_sel_hi:[1,0] neg_lo:[1,0] neg_hi:[1,0]
	v_pk_add_f32 v[142:143], v[78:79], 1.0 op_sel_hi:[1,0] neg_lo:[1,0] neg_hi:[1,0]
	v_pk_add_f32 v[226:227], v[80:81], 1.0 op_sel_hi:[1,0] neg_lo:[1,0] neg_hi:[1,0]
	v_pk_add_f32 v[228:229], v[82:83], 1.0 op_sel_hi:[1,0] neg_lo:[1,0] neg_hi:[1,0]
	v_pk_mul_f32 v[144:145], v[140:141], v[226:227]
	v_pk_mul_f32 v[146:147], v[142:143], v[228:229]
	v_pk_add_f32 v[230:231], v[84:85], 1.0 op_sel_hi:[1,0] neg_lo:[1,0] neg_hi:[1,0]
	v_pk_add_f32 v[232:233], v[86:87], 1.0 op_sel_hi:[1,0] neg_lo:[1,0] neg_hi:[1,0]
	v_pk_mul_f32 v[148:149], v[144:145], v[230:231]
	v_pk_mul_f32 v[150:151], v[146:147], v[232:233]
	v_pk_add_f32 v[234:235], v[88:89], 1.0 op_sel_hi:[1,0] neg_lo:[1,0] neg_hi:[1,0]
	v_pk_add_f32 v[236:237], v[90:91], 1.0 op_sel_hi:[1,0] neg_lo:[1,0] neg_hi:[1,0]
	v_pk_mul_f32 v[152:153], v[148:149], v[234:235]
	v_pk_mul_f32 v[154:155], v[150:151], v[236:237]
	v_pk_add_f32 v[238:239], v[92:93], 1.0 op_sel_hi:[1,0] neg_lo:[1,0] neg_hi:[1,0]
	v_pk_add_f32 v[240:241], v[94:95], 1.0 op_sel_hi:[1,0] neg_lo:[1,0] neg_hi:[1,0]
	v_pk_mul_f32 v[156:157], v[152:153], v[238:239]
	v_pk_mul_f32 v[158:159], v[154:155], v[240:241]
	v_pk_add_f32 v[242:243], v[96:97], 1.0 op_sel_hi:[1,0] neg_lo:[1,0] neg_hi:[1,0]
	v_pk_add_f32 v[244:245], v[98:99], 1.0 op_sel_hi:[1,0] neg_lo:[1,0] neg_hi:[1,0]
	v_pk_mul_f32 v[160:161], v[156:157], v[242:243]
	v_pk_mul_f32 v[162:163], v[158:159], v[244:245]
	v_pk_add_f32 v[246:247], v[100:101], 1.0 op_sel_hi:[1,0] neg_lo:[1,0] neg_hi:[1,0]
	v_pk_add_f32 v[248:249], v[102:103], 1.0 op_sel_hi:[1,0] neg_lo:[1,0] neg_hi:[1,0]
	v_pk_mul_f32 v[164:165], v[160:161], v[246:247]
	v_pk_mul_f32 v[166:167], v[162:163], v[248:249]
	v_pk_add_f32 v[74:75], v[104:105], 1.0 op_sel_hi:[1,0] neg_lo:[1,0] neg_hi:[1,0]
	v_pk_add_f32 v[172:173], v[106:107], 1.0 op_sel_hi:[1,0] neg_lo:[1,0] neg_hi:[1,0]
	v_pk_mul_f32 v[168:169], v[164:165], v[74:75]
	v_pk_mul_f32 v[170:171], v[166:167], v[172:173]
	s_waitcnt lgkmcnt(0)
	s_barrier
	s_cmp_eq_u32 s17, 0
	s_cbranch_scc1 .Lhg_pend
	v_lshlrev_b32_e32 v108, 16, v26
	v_and_b32_e32 v109, 0xffff0000, v26
	v_lshlrev_b32_e32 v110, 16, v27
	v_and_b32_e32 v111, 0xffff0000, v27
	v_lshlrev_b32_e32 v112, 16, v28
	v_and_b32_e32 v113, 0xffff0000, v28
	v_lshlrev_b32_e32 v114, 16, v29
	v_and_b32_e32 v115, 0xffff0000, v29
	v_lshlrev_b32_e32 v116, 16, v30
	v_and_b32_e32 v117, 0xffff0000, v30
	v_lshlrev_b32_e32 v118, 16, v31
	v_and_b32_e32 v119, 0xffff0000, v31
	v_lshlrev_b32_e32 v120, 16, v32
	v_and_b32_e32 v121, 0xffff0000, v32
	v_lshlrev_b32_e32 v122, 16, v33
	v_and_b32_e32 v123, 0xffff0000, v33
	v_lshlrev_b32_e32 v124, 16, v34
	v_and_b32_e32 v125, 0xffff0000, v34
	v_lshlrev_b32_e32 v126, 16, v35
	v_and_b32_e32 v127, 0xffff0000, v35
	v_lshlrev_b32_e32 v128, 16, v36
	v_and_b32_e32 v129, 0xffff0000, v36
	v_lshlrev_b32_e32 v130, 16, v37
	v_and_b32_e32 v131, 0xffff0000, v37
	v_lshlrev_b32_e32 v132, 16, v38
	v_and_b32_e32 v133, 0xffff0000, v38
	v_lshlrev_b32_e32 v134, 16, v39
	v_and_b32_e32 v135, 0xffff0000, v39
	v_lshlrev_b32_e32 v136, 16, v40
	v_and_b32_e32 v137, 0xffff0000, v40
	v_lshlrev_b32_e32 v138, 16, v41
	v_and_b32_e32 v139, 0xffff0000, v41
	global_load_dwordx2 v[10:11], v3, s[8:9]
	global_load_dwordx2 v[26:27], v2, s[8:9]
	s_add_u32 s8, s8, s10
	s_addc_u32 s9, s9, s11
	global_load_dwordx2 v[12:13], v3, s[8:9]
	global_load_dwordx2 v[28:29], v2, s[8:9]
	s_add_u32 s8, s8, s10
	s_addc_u32 s9, s9, s11
	global_load_dwordx2 v[14:15], v3, s[8:9]
	global_load_dwordx2 v[30:31], v2, s[8:9]
	s_add_u32 s8, s8, s10
	s_addc_u32 s9, s9, s11
	global_load_dwordx2 v[16:17], v3, s[8:9]
	global_load_dwordx2 v[32:33], v2, s[8:9]
	s_add_u32 s8, s8, s10
	s_addc_u32 s9, s9, s11
	global_load_dwordx2 v[18:19], v3, s[8:9]
	global_load_dwordx2 v[34:35], v2, s[8:9]
	s_add_u32 s8, s8, s10
	s_addc_u32 s9, s9, s11
	global_load_dwordx2 v[20:21], v3, s[8:9]
	global_load_dwordx2 v[36:37], v2, s[8:9]
	s_add_u32 s8, s8, s10
	s_addc_u32 s9, s9, s11
	global_load_dwordx2 v[22:23], v3, s[8:9]
	global_load_dwordx2 v[38:39], v2, s[8:9]
	s_add_u32 s8, s8, s10
	s_addc_u32 s9, s9, s11
	global_load_dwordx2 v[24:25], v3, s[8:9]
	global_load_dwordx2 v[40:41], v2, s[8:9]
	s_add_u32 s8, s8, s10
	s_addc_u32 s9, s9, s11
	s_cmp_lt_u32 s16, 63
	s_cselect_b32 s34, s12, s14
	s_cselect_b32 s35, s13, s15
	s_add_u32 s8, s8, s34
	s_addc_u32 s9, s9, s35
	s_add_i32 s16, s16, 1
	v_mov_b32_e32 v176, 1.0
	v_mov_b32_e32 v177, 1.0
	v_mov_b32_e32 v178, 1.0
	v_mov_b32_e32 v179, 1.0
	v_mul_f32_dpp v196, v168, v168 row_ror:8 row_mask:0xf bank_mask:0xf
	v_mul_f32_dpp v197, v169, v169 row_ror:8 row_mask:0xf bank_mask:0xf
	v_mul_f32_dpp v198, v170, v170 row_ror:8 row_mask:0xf bank_mask:0xf
	v_mul_f32_dpp v199, v171, v171 row_ror:8 row_mask:0xf bank_mask:0xf
	v_mov_b32_dpp v176, v168 row_shr:8 row_mask:0xf bank_mask:0xc
	v_mov_b32_dpp v177, v169 row_shr:8 row_mask:0xf bank_mask:0xc
	v_mov_b32_dpp v178, v170 row_shr:8 row_mask:0xf bank_mask:0xc
	v_mov_b32_dpp v179, v171 row_shr:8 row_mask:0xf bank_mask:0xc
	v_mov_b32_e32 v200, v196
	v_mov_b32_e32 v201, v197
	v_mov_b32_e32 v202, v198
	v_mov_b32_e32 v203, v199
	v_permlane16_swap_b32_e32 v196, v200
	v_permlane16_swap_b32_e32 v197, v201
	v_permlane16_swap_b32_e32 v198, v202
	v_permlane16_swap_b32_e32 v199, v203
	v_pk_mul_f32 v[204:205], v[196:197], v[200:201]
	v_pk_mul_f32 v[206:207], v[198:199], v[202:203]
	v_mov_b32_e32 v208, v204
	v_mov_b32_e32 v209, v205
	v_mov_b32_e32 v210, v206
	v_mov_b32_e32 v211, v207
	s_nop 0
	v_permlane32_swap_b32_e32 v204, v208
	v_permlane32_swap_b32_e32 v205, v209
	v_permlane32_swap_b32_e32 v206, v210
	v_permlane32_swap_b32_e32 v207, v211
	s_mov_b64 s[34:35], exec
	s_mov_b64 exec, 0xffff0000
	v_pk_mul_f32 v[176:177], v[176:177], v[196:197]
	v_pk_mul_f32 v[178:179], v[178:179], v[198:199]
	s_mov_b32 exec_lo, 0
	s_mov_b32 exec_hi, -1
	v_pk_mul_f32 v[176:177], v[176:177], v[204:205]
	v_pk_mul_f32 v[178:179], v[178:179], v[206:207]
	s_mov_b32 exec_hi, 0xffff0000
	v_pk_mul_f32 v[176:177], v[176:177], v[196:197]
	v_pk_mul_f32 v[178:179], v[178:179], v[198:199]
	s_mov_b64 exec, s[34:35]
	v_pk_mul_f32 v[188:189], v[176:177], v[168:169]
	v_pk_mul_f32 v[190:191], v[178:179], v[170:171]
	s_mov_b64 s[34:35], exec
	s_mov_b64 exec, s[30:31]
	ds_write_b128 v8, v[188:191]
	s_mov_b64 exec, s[34:35]
	v_max_f32_e32 v180, 0xda24260, v188
	v_max_f32_e32 v181, 0xda24260, v189
	v_max_f32_e32 v182, 0xda24260, v190
	v_max_f32_e32 v183, 0xda24260, v191
	v_rcp_f32_e32 v180, v180
	v_rcp_f32_e32 v181, v181
	v_rcp_f32_e32 v182, v182
	v_rcp_f32_e32 v183, v183
	v_pk_mul_f32 v[192:193], v[136:137], v[188:189]
	v_pk_mul_f32 v[194:195], v[138:139], v[190:191]
	v_pk_mul_f32 v[196:197], v[104:105], v[180:181]
	v_pk_mul_f32 v[198:199], v[106:107], v[182:183]
	v_cvt_pk_bf16_f32 v208, v192, v193
	v_cvt_pk_bf16_f32 v209, v194, v195
	v_cvt_pk_bf16_f32 v210, v196, v197
	v_cvt_pk_bf16_f32 v211, v198, v199
	v_pk_mul_f32 v[180:181], v[180:181], v[74:75]
	v_pk_mul_f32 v[182:183], v[182:183], v[172:173]
	v_pk_mul_f32 v[188:189], v[176:177], v[164:165]
	v_pk_mul_f32 v[190:191], v[178:179], v[166:167]
	v_pk_mul_f32 v[192:193], v[132:133], v[188:189]
	v_pk_mul_f32 v[194:195], v[134:135], v[190:191]
	v_pk_mul_f32 v[200:201], v[100:101], v[180:181]
	v_pk_mul_f32 v[202:203], v[102:103], v[182:183]
	v_cvt_pk_bf16_f32 v204, v192, v193
	v_cvt_pk_bf16_f32 v205, v194, v195
	v_cvt_pk_bf16_f32 v206, v200, v201
	v_cvt_pk_bf16_f32 v207, v202, v203
	ds_write2_b64 v4, v[204:205], v[208:209] offset0:216 offset1:252
	ds_write2_b64 v7, v[206:207], v[210:211] offset0:216 offset1:252
	v_pk_mul_f32 v[180:181], v[180:181], v[246:247]
	v_pk_mul_f32 v[182:183], v[182:183], v[248:249]
	v_pk_mul_f32 v[188:189], v[176:177], v[160:161]
	v_pk_mul_f32 v[190:191], v[178:179], v[162:163]
	v_pk_mul_f32 v[192:193], v[128:129], v[188:189]
	v_pk_mul_f32 v[194:195], v[130:131], v[190:191]
	v_pk_mul_f32 v[196:197], v[96:97], v[180:181]
	v_pk_mul_f32 v[198:199], v[98:99], v[182:183]
	v_cvt_pk_bf16_f32 v208, v192, v193
	v_cvt_pk_bf16_f32 v209, v194, v195
	v_cvt_pk_bf16_f32 v210, v196, v197
	v_cvt_pk_bf16_f32 v211, v198, v199
	v_pk_mul_f32 v[180:181], v[180:181], v[242:243]
	v_pk_mul_f32 v[182:183], v[182:183], v[244:245]
	v_pk_mul_f32 v[188:189], v[176:177], v[156:157]
	v_pk_mul_f32 v[190:191], v[178:179], v[158:159]
	v_pk_mul_f32 v[192:193], v[124:125], v[188:189]
	v_pk_mul_f32 v[194:195], v[126:127], v[190:191]
	v_pk_mul_f32 v[200:201], v[92:93], v[180:181]
	v_pk_mul_f32 v[202:203], v[94:95], v[182:183]
	v_cvt_pk_bf16_f32 v204, v192, v193
	v_cvt_pk_bf16_f32 v205, v194, v195
	v_cvt_pk_bf16_f32 v206, v200, v201
	v_cvt_pk_bf16_f32 v207, v202, v203
	ds_write2_b64 v4, v[204:205], v[208:209] offset0:144 offset1:180
	ds_write2_b64 v7, v[206:207], v[210:211] offset0:144 offset1:180
	v_pk_mul_f32 v[180:181], v[180:181], v[238:239]
	v_pk_mul_f32 v[182:183], v[182:183], v[240:241]
	v_pk_mul_f32 v[188:189], v[176:177], v[152:153]
	v_pk_mul_f32 v[190:191], v[178:179], v[154:155]
	v_pk_mul_f32 v[192:193], v[120:121], v[188:189]
	v_pk_mul_f32 v[194:195], v[122:123], v[190:191]
	v_pk_mul_f32 v[196:197], v[88:89], v[180:181]
	v_pk_mul_f32 v[198:199], v[90:91], v[182:183]
	v_cvt_pk_bf16_f32 v208, v192, v193
	v_cvt_pk_bf16_f32 v209, v194, v195
	v_cvt_pk_bf16_f32 v210, v196, v197
	v_cvt_pk_bf16_f32 v211, v198, v199
	v_pk_mul_f32 v[180:181], v[180:181], v[234:235]
	v_pk_mul_f32 v[182:183], v[182:183], v[236:237]
	v_pk_mul_f32 v[188:189], v[176:177], v[148:149]
	v_pk_mul_f32 v[190:191], v[178:179], v[150:151]
	v_pk_mul_f32 v[192:193], v[116:117], v[188:189]
	v_pk_mul_f32 v[194:195], v[118:119], v[190:191]
	v_pk_mul_f32 v[200:201], v[84:85], v[180:181]
	v_pk_mul_f32 v[202:203], v[86:87], v[182:183]
	v_cvt_pk_bf16_f32 v204, v192, v193
	v_cvt_pk_bf16_f32 v205, v194, v195
	v_cvt_pk_bf16_f32 v206, v200, v201
	v_cvt_pk_bf16_f32 v207, v202, v203
	ds_write2_b64 v4, v[204:205], v[208:209] offset0:72 offset1:108
	ds_write2_b64 v7, v[206:207], v[210:211] offset0:72 offset1:108
	v_pk_mul_f32 v[180:181], v[180:181], v[230:231]
	v_pk_mul_f32 v[182:183], v[182:183], v[232:233]
	v_pk_mul_f32 v[188:189], v[176:177], v[144:145]
	v_pk_mul_f32 v[190:191], v[178:179], v[146:147]
	v_pk_mul_f32 v[192:193], v[112:113], v[188:189]
	v_pk_mul_f32 v[194:195], v[114:115], v[190:191]
	v_pk_mul_f32 v[196:197], v[80:81], v[180:181]
	v_pk_mul_f32 v[198:199], v[82:83], v[182:183]
	v_cvt_pk_bf16_f32 v208, v192, v193
	v_cvt_pk_bf16_f32 v209, v194, v195
	v_cvt_pk_bf16_f32 v210, v196, v197
	v_cvt_pk_bf16_f32 v211, v198, v199
	v_pk_mul_f32 v[180:181], v[180:181], v[226:227]
	v_pk_mul_f32 v[182:183], v[182:183], v[228:229]
	v_pk_mul_f32 v[188:189], v[176:177], v[140:141]
	v_pk_mul_f32 v[190:191], v[178:179], v[142:143]
	v_pk_mul_f32 v[192:193], v[108:109], v[188:189]
	v_pk_mul_f32 v[194:195], v[110:111], v[190:191]
	v_pk_mul_f32 v[200:201], v[76:77], v[180:181]
	v_pk_mul_f32 v[202:203], v[78:79], v[182:183]
	v_cvt_pk_bf16_f32 v204, v192, v193
	v_cvt_pk_bf16_f32 v205, v194, v195
	v_cvt_pk_bf16_f32 v206, v200, v201
	v_cvt_pk_bf16_f32 v207, v202, v203
	ds_write2_b64 v4, v[204:205], v[208:209] offset0:0 offset1:36
	ds_write2_b64 v7, v[206:207], v[210:211] offset0:0 offset1:36
	s_waitcnt vmcnt(16)
	v_lshlrev_b32_e32 v76, 16, v42
	v_and_b32_e32 v77, 0xffff0000, v42
	v_lshlrev_b32_e32 v78, 16, v43
	v_and_b32_e32 v79, 0xffff0000, v43
	v_lshlrev_b32_e32 v80, 16, v44
	v_and_b32_e32 v81, 0xffff0000, v44
	v_lshlrev_b32_e32 v82, 16, v45
	v_and_b32_e32 v83, 0xffff0000, v45
	v_lshlrev_b32_e32 v84, 16, v46
	v_and_b32_e32 v85, 0xffff0000, v46
	v_lshlrev_b32_e32 v86, 16, v47
	v_and_b32_e32 v87, 0xffff0000, v47
	v_lshlrev_b32_e32 v88, 16, v48
	v_and_b32_e32 v89, 0xffff0000, v48
	v_lshlrev_b32_e32 v90, 16, v49
	v_and_b32_e32 v91, 0xffff0000, v49
	v_lshlrev_b32_e32 v92, 16, v50
	v_and_b32_e32 v93, 0xffff0000, v50
	v_lshlrev_b32_e32 v94, 16, v51
	v_and_b32_e32 v95, 0xffff0000, v51
	v_lshlrev_b32_e32 v96, 16, v52
	v_and_b32_e32 v97, 0xffff0000, v52
	v_lshlrev_b32_e32 v98, 16, v53
	v_and_b32_e32 v99, 0xffff0000, v53
	v_lshlrev_b32_e32 v100, 16, v54
	v_and_b32_e32 v101, 0xffff0000, v54
	v_lshlrev_b32_e32 v102, 16, v55
	v_and_b32_e32 v103, 0xffff0000, v55
	v_lshlrev_b32_e32 v104, 16, v56
	v_and_b32_e32 v105, 0xffff0000, v56
	v_lshlrev_b32_e32 v106, 16, v57
	v_and_b32_e32 v107, 0xffff0000, v57
	v_pk_add_f32 v[140:141], v[76:77], 1.0 op_sel_hi:[1,0] neg_lo:[1,0] neg_hi:[1,0]
	v_pk_add_f32 v[142:143], v[78:79], 1.0 op_sel_hi:[1,0] neg_lo:[1,0] neg_hi:[1,0]
	v_pk_add_f32 v[226:227], v[80:81], 1.0 op_sel_hi:[1,0] neg_lo:[1,0] neg_hi:[1,0]
	v_pk_add_f32 v[228:229], v[82:83], 1.0 op_sel_hi:[1,0] neg_lo:[1,0] neg_hi:[1,0]
	v_pk_mul_f32 v[144:145], v[140:141], v[226:227]
	v_pk_mul_f32 v[146:147], v[142:143], v[228:229]
	v_pk_add_f32 v[230:231], v[84:85], 1.0 op_sel_hi:[1,0] neg_lo:[1,0] neg_hi:[1,0]
	v_pk_add_f32 v[232:233], v[86:87], 1.0 op_sel_hi:[1,0] neg_lo:[1,0] neg_hi:[1,0]
	v_pk_mul_f32 v[148:149], v[144:145], v[230:231]
	v_pk_mul_f32 v[150:151], v[146:147], v[232:233]
	v_pk_add_f32 v[234:235], v[88:89], 1.0 op_sel_hi:[1,0] neg_lo:[1,0] neg_hi:[1,0]
	v_pk_add_f32 v[236:237], v[90:91], 1.0 op_sel_hi:[1,0] neg_lo:[1,0] neg_hi:[1,0]
	v_pk_mul_f32 v[152:153], v[148:149], v[234:235]
	v_pk_mul_f32 v[154:155], v[150:151], v[236:237]
	v_pk_add_f32 v[238:239], v[92:93], 1.0 op_sel_hi:[1,0] neg_lo:[1,0] neg_hi:[1,0]
	v_pk_add_f32 v[240:241], v[94:95], 1.0 op_sel_hi:[1,0] neg_lo:[1,0] neg_hi:[1,0]
	v_pk_mul_f32 v[156:157], v[152:153], v[238:239]
	v_pk_mul_f32 v[158:159], v[154:155], v[240:241]
	v_pk_add_f32 v[242:243], v[96:97], 1.0 op_sel_hi:[1,0] neg_lo:[1,0] neg_hi:[1,0]
	v_pk_add_f32 v[244:245], v[98:99], 1.0 op_sel_hi:[1,0] neg_lo:[1,0] neg_hi:[1,0]
	v_pk_mul_f32 v[160:161], v[156:157], v[242:243]
	v_pk_mul_f32 v[162:163], v[158:159], v[244:245]
	v_pk_add_f32 v[246:247], v[100:101], 1.0 op_sel_hi:[1,0] neg_lo:[1,0] neg_hi:[1,0]
	v_pk_add_f32 v[248:249], v[102:103], 1.0 op_sel_hi:[1,0] neg_lo:[1,0] neg_hi:[1,0]
	v_pk_mul_f32 v[164:165], v[160:161], v[246:247]
	v_pk_mul_f32 v[166:167], v[162:163], v[248:249]
	v_pk_add_f32 v[74:75], v[104:105], 1.0 op_sel_hi:[1,0] neg_lo:[1,0] neg_hi:[1,0]
	v_pk_add_f32 v[172:173], v[106:107], 1.0 op_sel_hi:[1,0] neg_lo:[1,0] neg_hi:[1,0]
	v_pk_mul_f32 v[168:169], v[164:165], v[74:75]
	v_pk_mul_f32 v[170:171], v[166:167], v[172:173]
	s_waitcnt lgkmcnt(0)
	s_barrier
	s_add_i32 s17, s17, -1
	s_branch .Lhg_ploop
